# grid barrier: the waiting lane issues its L1 invalidate (buffer_inv sc1) before spinning on the release word instead of after; no load is issued by the workgroup in between, so the acquire is unchange
# speedup vs baseline: 1.0001x; 1.0001x over previous
; __device__ __forceinline__ unsigned xb_ld(unsigned* p)              { return __hip_atomic_load(p, __ATOMIC_RELAXED, __HIP_MEMORY_SCOPE_AGENT); }
; __device__ __forceinline__ unsigned xb_add(unsigned* p, unsigned v) { return __hip_atomic_fetch_add(p, v, __ATOMIC_RELAXED, __HIP_MEMORY_SCOPE_AGENT); }
; #define XB_SPIN(cond, bar) do { unsigned _sp = 0; while (cond) { __builtin_amdgcn_s_sleep(1); \
;     if ((++_sp & 255u) == 0u) { if (xb_ld(&(bar)[XB_TMO])) break; if (_sp > XB_SPIN_CAP) { atomicAdd(&(bar)[XB_TMO], 1u); break; } } } } while (0)
; __device__ __forceinline__ void xcd_barrier(const XcdBarrier& b) {
;     ...
;         unsigned nloc = b.st[0], nx = b.st[1];
;         if (nloc == 0u) { xcd_barrier_complete(bar, b.x, nloc, nx); b.st[0] = nloc; b.st[1] = nx; }
;         const unsigned old = xb_add(&bar[XB_XSUB(b.x)], 1u);
;         const unsigned gen = old / nloc;
;         if (old + 1u == (gen + 1u) * nloc) {
;             __builtin_amdgcn_fence(__ATOMIC_RELEASE, "agent");
;             asm volatile("s_waitcnt vmcnt(0)" ::: "memory");
;             const unsigned og = xb_add(&bar[XB_TOP], 1u);
;             const unsigned tg = og / nx;
;             if (og + 1u == (tg + 1u) * nx) xb_add(&bar[XB_TOPGEN], 1u);
;             else XB_SPIN(xb_ld(&bar[XB_TOPGEN]) == tg, bar);
;             __builtin_amdgcn_fence(__ATOMIC_ACQUIRE, "agent");
;             xb_add(&bar[XB_XGEN(b.x)], 1u);
;             asm volatile("s_waitcnt vmcnt(0)" ::: "memory");
;         } else {
;             XB_SPIN(xb_ld(&bar[XB_XGEN(b.x)]) == gen, bar);
.LBB0_86:
	s_or_b64 exec, exec, s[10:11]
	v_cvt_f32_u32_e32 v4, v2
	s_waitcnt vmcnt(0)
	v_readfirstlane_b32 s8, v3
	v_sub_u32_e32 v3, 0, v2
	v_rcp_iflag_f32_e32 v4, v4
	v_add_u32_e32 v5, s8, v1
	v_mul_f32_e32 v4, 0x4f7ffffe, v4
	v_cvt_u32_f32_e32 v4, v4
	v_mul_lo_u32 v1, v3, v4
	v_mul_hi_u32 v1, v4, v1
	v_add_u32_e32 v1, v4, v1
	v_mul_hi_u32 v1, v5, v1
	v_mul_lo_u32 v3, v1, v2
	v_sub_u32_e32 v3, v5, v3
	v_add_u32_e32 v4, 1, v1
	v_cmp_ge_u32_e32 vcc, v3, v2
	s_nop 1
	v_cndmask_b32_e32 v1, v1, v4, vcc
	v_sub_u32_e32 v4, v3, v2
	v_cndmask_b32_e32 v3, v3, v4, vcc
	v_add_u32_e32 v4, 1, v1
	v_cmp_ge_u32_e32 vcc, v3, v2
	v_add_u32_e32 v3, 1, v5
	s_nop 0
	v_cndmask_b32_e32 v1, v1, v4, vcc
	v_mul_lo_u32 v4, v2, v1
	v_add_u32_e32 v2, v4, v2
	v_cmp_ne_u32_e32 vcc, v3, v2
	s_and_saveexec_b64 s[8:9], vcc
	s_xor_b64 s[8:9], exec, s[8:9]
	s_cbranch_execz .LBB0_100
	s_waitcnt lgkmcnt(0)
	v_mov_b32_e32 v0, 0x2000
	buffer_inv sc1
	global_load_dword v0, v0, s[6:7] offset:1024 sc1
	s_add_u32 s16, s6, 0x2400
	s_addc_u32 s17, s7, 0
	s_waitcnt vmcnt(0)
	v_cmp_eq_u32_e32 vcc, v0, v1
	s_and_saveexec_b64 s[10:11], vcc
	s_cbranch_execz .LBB0_99
	s_add_u32 s14, s64, 0x4200
	s_addc_u32 s15, s65, 0
	s_mov_b32 s28, 1
	s_mov_b64 s[18:19], 0
	v_mov_b32_e32 v0, 0
	s_branch .LBB0_90

; __device__ __forceinline__ unsigned xb_ld(unsigned* p)              { return __hip_atomic_load(p, __ATOMIC_RELAXED, __HIP_MEMORY_SCOPE_AGENT); }
; #define XB_SPIN(cond, bar) do { unsigned _sp = 0; while (cond) { __builtin_amdgcn_s_sleep(1); \
;     if ((++_sp & 255u) == 0u) { if (xb_ld(&(bar)[XB_TMO])) break; if (_sp > XB_SPIN_CAP) { atomicAdd(&(bar)[XB_TMO], 1u); break; } } } } while (0)
; __device__ __forceinline__ void xcd_barrier(const XcdBarrier& b) {
;     ...
;             XB_SPIN(xb_ld(&bar[XB_XGEN(b.x)]) == gen, bar);
;             __builtin_amdgcn_fence(__ATOMIC_ACQUIRE, "agent");
;             asm volatile("s_waitcnt vmcnt(0)" ::: "memory");
.LBB0_99:
	s_or_b64 exec, exec, s[10:11]
	s_waitcnt vmcnt(0)
	s_nop 0
	s_waitcnt vmcnt(0)

; __device__ __forceinline__ unsigned xb_ld(unsigned* p)              { return __hip_atomic_load(p, __ATOMIC_RELAXED, __HIP_MEMORY_SCOPE_AGENT); }
; __device__ __forceinline__ unsigned xb_add(unsigned* p, unsigned v) { return __hip_atomic_fetch_add(p, v, __ATOMIC_RELAXED, __HIP_MEMORY_SCOPE_AGENT); }
; #define XB_SPIN(cond, bar) do { unsigned _sp = 0; while (cond) { __builtin_amdgcn_s_sleep(1); \
;     if ((++_sp & 255u) == 0u) { if (xb_ld(&(bar)[XB_TMO])) break; if (_sp > XB_SPIN_CAP) { atomicAdd(&(bar)[XB_TMO], 1u); break; } } } } while (0)
; __device__ __forceinline__ void xcd_barrier(const XcdBarrier& b) {
;     ...
;             asm volatile("s_waitcnt vmcnt(0)" ::: "memory");
;             const unsigned og = xb_add(&bar[XB_TOP], 1u);
;             const unsigned tg = og / nx;
;             if (og + 1u == (tg + 1u) * nx) xb_add(&bar[XB_TOPGEN], 1u);
;             else XB_SPIN(xb_ld(&bar[XB_TOPGEN]) == tg, bar);
.LBB0_103:
	s_or_b64 exec, exec, s[10:11]
	v_cvt_f32_u32_e32 v3, v0
	s_waitcnt vmcnt(0)
	buffer_inv sc1
	v_readfirstlane_b32 s8, v2
	s_add_u32 s10, s64, 0x7500
	s_addc_u32 s11, s65, 0
	v_rcp_iflag_f32_e32 v3, v3
	v_add_u32_e32 v1, s8, v1
	v_add_u32_e32 v4, 1, v1
	s_mov_b64 s[14:15], -1
	v_mul_f32_e32 v2, 0x4f7ffffe, v3
	v_cvt_u32_f32_e32 v2, v2
	v_sub_u32_e32 v3, 0, v0
	v_mul_lo_u32 v3, v3, v2
	v_mul_hi_u32 v3, v2, v3
	v_add_u32_e32 v2, v2, v3
	v_mul_hi_u32 v2, v1, v2
	v_mul_lo_u32 v3, v2, v0
	v_sub_u32_e32 v1, v1, v3
	v_add_u32_e32 v5, 1, v2
	v_cmp_ge_u32_e32 vcc, v1, v0
	v_sub_u32_e32 v3, v1, v0
	s_nop 0
	v_cndmask_b32_e32 v2, v2, v5, vcc
	v_cndmask_b32_e32 v1, v1, v3, vcc
	v_add_u32_e32 v3, 1, v2
	v_cmp_ge_u32_e32 vcc, v1, v0
	s_nop 1
	v_cndmask_b32_e32 v2, v2, v3, vcc
	v_mul_lo_u32 v1, v0, v2
	v_add_u32_e32 v0, v1, v0
	v_cmp_ne_u32_e32 vcc, v4, v0
	v_mov_b64_e32 v[0:1], s[10:11]
	s_and_saveexec_b64 s[8:9], vcc
	s_cbranch_execz .LBB0_115
	v_mov_b32_e32 v0, 0
	global_load_dword v1, v0, s[10:11] sc1
	s_mov_b64 s[18:19], 0
	s_waitcnt vmcnt(0)
	v_cmp_eq_u32_e32 vcc, v1, v2
	s_and_saveexec_b64 s[16:17], vcc
	s_cbranch_execz .LBB0_114
	s_add_u32 s14, s64, 0x4200
	s_addc_u32 s15, s65, 0
	s_mov_b32 s28, 1
	s_branch .LBB0_107

; __device__ __forceinline__ unsigned xb_add(unsigned* p, unsigned v) { return __hip_atomic_fetch_add(p, v, __ATOMIC_RELAXED, __HIP_MEMORY_SCOPE_AGENT); }
; __device__ __forceinline__ void xcd_barrier(const XcdBarrier& b) {
;     ...
;             __builtin_amdgcn_fence(__ATOMIC_ACQUIRE, "agent");
;             xb_add(&bar[XB_XGEN(b.x)], 1u);
;             asm volatile("s_waitcnt vmcnt(0)" ::: "memory");
.LBB0_117:
	s_or_b64 exec, exec, s[8:9]
	s_mov_b64 s[8:9], exec
	v_mbcnt_lo_u32_b32 v0, s8, 0
	v_mbcnt_hi_u32_b32 v0, s9, v0
	v_cmp_eq_u32_e32 vcc, 0, v0
	s_waitcnt vmcnt(0)
	s_nop 0
	s_and_saveexec_b64 s[10:11], vcc
	s_cbranch_execz .LBB0_119
	s_bcnt1_i32_b64 s8, s[8:9]
	v_mov_b32_e32 v0, 0x2000
	v_mov_b32_e32 v1, s8
	global_atomic_add v0, v1, s[6:7] offset:1024

; __device__ __forceinline__ unsigned xb_ld(unsigned* p)              { return __hip_atomic_load(p, __ATOMIC_RELAXED, __HIP_MEMORY_SCOPE_AGENT); }
; __device__ __forceinline__ unsigned xb_add(unsigned* p, unsigned v) { return __hip_atomic_fetch_add(p, v, __ATOMIC_RELAXED, __HIP_MEMORY_SCOPE_AGENT); }
; #define XB_SPIN(cond, bar) do { unsigned _sp = 0; while (cond) { __builtin_amdgcn_s_sleep(1); \
;     if ((++_sp & 255u) == 0u) { if (xb_ld(&(bar)[XB_TMO])) break; if (_sp > XB_SPIN_CAP) { atomicAdd(&(bar)[XB_TMO], 1u); break; } } } } while (0)
; __device__ __forceinline__ void xcd_barrier(const XcdBarrier& b) {
;     ...
;         const unsigned old = xb_add(&bar[XB_XSUB(b.x)], 1u);
;         const unsigned gen = old / nloc;
;         if (old + 1u == (gen + 1u) * nloc) {
;             __builtin_amdgcn_fence(__ATOMIC_RELEASE, "agent");
;             asm volatile("s_waitcnt vmcnt(0)" ::: "memory");
;             const unsigned og = xb_add(&bar[XB_TOP], 1u);
;             const unsigned tg = og / nx;
;             if (og + 1u == (tg + 1u) * nx) xb_add(&bar[XB_TOPGEN], 1u);
;             else XB_SPIN(xb_ld(&bar[XB_TOPGEN]) == tg, bar);
;             __builtin_amdgcn_fence(__ATOMIC_ACQUIRE, "agent");
;             xb_add(&bar[XB_XGEN(b.x)], 1u);
;             asm volatile("s_waitcnt vmcnt(0)" ::: "memory");
;         } else {
;             XB_SPIN(xb_ld(&bar[XB_XGEN(b.x)]) == gen, bar);
.LBB0_195:
	s_or_b64 exec, exec, s[38:39]
	v_cvt_f32_u32_e32 v4, v2
	s_waitcnt vmcnt(0)
	v_readfirstlane_b32 s5, v3
	v_sub_u32_e32 v3, 0, v2
	v_rcp_iflag_f32_e32 v4, v4
	v_add_u32_e32 v5, s5, v1
	v_mul_f32_e32 v4, 0x4f7ffffe, v4
	v_cvt_u32_f32_e32 v4, v4
	v_mul_lo_u32 v1, v3, v4
	v_mul_hi_u32 v1, v4, v1
	v_add_u32_e32 v1, v4, v1
	v_mul_hi_u32 v1, v5, v1
	v_mul_lo_u32 v3, v1, v2
	v_sub_u32_e32 v3, v5, v3
	v_add_u32_e32 v4, 1, v1
	v_cmp_ge_u32_e32 vcc, v3, v2
	s_nop 1
	v_cndmask_b32_e32 v1, v1, v4, vcc
	v_sub_u32_e32 v4, v3, v2
	v_cndmask_b32_e32 v3, v3, v4, vcc
	v_add_u32_e32 v4, 1, v1
	v_cmp_ge_u32_e32 vcc, v3, v2
	v_add_u32_e32 v3, 1, v5
	s_nop 0
	v_cndmask_b32_e32 v1, v1, v4, vcc
	v_mul_lo_u32 v4, v2, v1
	v_add_u32_e32 v2, v4, v2
	v_cmp_ne_u32_e32 vcc, v3, v2
	s_and_saveexec_b64 s[6:7], vcc
	s_xor_b64 s[38:39], exec, s[6:7]
	s_cbranch_execz .LBB0_209
	v_readlane_b32 s6, v254, 62
	v_readlane_b32 s7, v254, 63
	s_waitcnt lgkmcnt(0)
	s_nop 3
	buffer_inv sc1
	global_load_dword v0, v193, s[6:7] sc1
	s_waitcnt vmcnt(0)
	v_cmp_eq_u32_e32 vcc, v0, v1
	s_and_saveexec_b64 s[40:41], vcc
	s_cbranch_execz .LBB0_208
	s_mov_b32 s5, 1
	s_mov_b64 s[42:43], 0
	s_branch .LBB0_199

; __device__ __forceinline__ unsigned xb_ld(unsigned* p)              { return __hip_atomic_load(p, __ATOMIC_RELAXED, __HIP_MEMORY_SCOPE_AGENT); }
; #define XB_SPIN(cond, bar) do { unsigned _sp = 0; while (cond) { __builtin_amdgcn_s_sleep(1); \
;     if ((++_sp & 255u) == 0u) { if (xb_ld(&(bar)[XB_TMO])) break; if (_sp > XB_SPIN_CAP) { atomicAdd(&(bar)[XB_TMO], 1u); break; } } } } while (0)
; __device__ __forceinline__ void xcd_barrier(const XcdBarrier& b) {
;     ...
;             XB_SPIN(xb_ld(&bar[XB_XGEN(b.x)]) == gen, bar);
;             __builtin_amdgcn_fence(__ATOMIC_ACQUIRE, "agent");
;             asm volatile("s_waitcnt vmcnt(0)" ::: "memory");
.LBB0_208:
	s_or_b64 exec, exec, s[40:41]
	s_waitcnt vmcnt(0)
	s_nop 0
	s_waitcnt vmcnt(0)

; __device__ __forceinline__ unsigned xb_ld(unsigned* p)              { return __hip_atomic_load(p, __ATOMIC_RELAXED, __HIP_MEMORY_SCOPE_AGENT); }
; __device__ __forceinline__ unsigned xb_add(unsigned* p, unsigned v) { return __hip_atomic_fetch_add(p, v, __ATOMIC_RELAXED, __HIP_MEMORY_SCOPE_AGENT); }
; #define XB_SPIN(cond, bar) do { unsigned _sp = 0; while (cond) { __builtin_amdgcn_s_sleep(1); \
;     if ((++_sp & 255u) == 0u) { if (xb_ld(&(bar)[XB_TMO])) break; if (_sp > XB_SPIN_CAP) { atomicAdd(&(bar)[XB_TMO], 1u); break; } } } } while (0)
; __device__ __forceinline__ void xcd_barrier(const XcdBarrier& b) {
;     ...
;             const unsigned og = xb_add(&bar[XB_TOP], 1u);
;             const unsigned tg = og / nx;
;             if (og + 1u == (tg + 1u) * nx) xb_add(&bar[XB_TOPGEN], 1u);
;             else XB_SPIN(xb_ld(&bar[XB_TOPGEN]) == tg, bar);
.LBB0_212:
	s_or_b64 exec, exec, s[40:41]
	s_waitcnt vmcnt(0)
	buffer_inv sc1
	v_readfirstlane_b32 s5, v2
	v_cvt_f32_u32_e32 v2, v0
	v_sub_u32_e32 v3, 0, v0
	v_add_u32_e32 v1, s5, v1
	v_readlane_b32 s6, v255, 2
	v_rcp_iflag_f32_e32 v2, v2
	v_readlane_b32 s7, v255, 3
	s_mov_b64 s[40:41], -1
	v_mul_f32_e32 v2, 0x4f7ffffe, v2
	v_cvt_u32_f32_e32 v2, v2
	v_mul_lo_u32 v3, v3, v2
	v_mul_hi_u32 v3, v2, v3
	v_add_u32_e32 v2, v2, v3
	v_mul_hi_u32 v2, v1, v2
	v_mul_lo_u32 v3, v2, v0
	v_sub_u32_e32 v3, v1, v3
	v_cmp_ge_u32_e32 vcc, v3, v0
	v_add_u32_e32 v4, 1, v2
	v_add_u32_e32 v1, 1, v1
	v_cndmask_b32_e32 v2, v2, v4, vcc
	v_sub_u32_e32 v4, v3, v0
	v_cndmask_b32_e32 v3, v3, v4, vcc
	v_cmp_ge_u32_e32 vcc, v3, v0
	v_add_u32_e32 v3, 1, v2
	s_nop 0
	v_cndmask_b32_e32 v2, v2, v3, vcc
	v_mul_lo_u32 v3, v0, v2
	v_add_u32_e32 v0, v3, v0
	v_cmp_ne_u32_e32 vcc, v1, v0
	v_mov_b64_e32 v[0:1], s[6:7]
	s_and_saveexec_b64 s[38:39], vcc
	s_cbranch_execz .LBB0_224
	v_readlane_b32 s6, v255, 2
	v_readlane_b32 s7, v255, 3
	s_mov_b64 s[42:43], 0
	s_nop 3
	global_load_dword v0, v193, s[6:7] sc1
	s_waitcnt vmcnt(0)
	v_cmp_eq_u32_e32 vcc, v0, v2
	s_and_saveexec_b64 s[40:41], vcc
	s_cbranch_execz .LBB0_223
	s_mov_b32 s5, 1
	s_branch .LBB0_216

; __device__ __forceinline__ unsigned xb_add(unsigned* p, unsigned v) { return __hip_atomic_fetch_add(p, v, __ATOMIC_RELAXED, __HIP_MEMORY_SCOPE_AGENT); }
; __device__ __forceinline__ void xcd_barrier(const XcdBarrier& b) {
;     ...
;             __builtin_amdgcn_fence(__ATOMIC_ACQUIRE, "agent");
;             xb_add(&bar[XB_XGEN(b.x)], 1u);
;             asm volatile("s_waitcnt vmcnt(0)" ::: "memory");
.LBB0_226:
	s_or_b64 exec, exec, s[38:39]
	s_mov_b64 s[38:39], exec
	v_mbcnt_lo_u32_b32 v0, s38, 0
	v_mbcnt_hi_u32_b32 v0, s39, v0
	v_cmp_eq_u32_e32 vcc, 0, v0
	s_waitcnt vmcnt(0)
	s_nop 0
	s_and_saveexec_b64 s[40:41], vcc
	s_cbranch_execz .LBB0_228
	s_bcnt1_i32_b64 s5, s[38:39]
	v_readlane_b32 s6, v254, 62
	v_mov_b32_e32 v0, s5
	v_readlane_b32 s7, v254, 63
	s_nop 4
	global_atomic_add v193, v0, s[6:7]

; __device__ __forceinline__ unsigned xb_ld(unsigned* p)              { return __hip_atomic_load(p, __ATOMIC_RELAXED, __HIP_MEMORY_SCOPE_AGENT); }
; __device__ __forceinline__ unsigned xb_add(unsigned* p, unsigned v) { return __hip_atomic_fetch_add(p, v, __ATOMIC_RELAXED, __HIP_MEMORY_SCOPE_AGENT); }
; #define XB_SPIN(cond, bar) do { unsigned _sp = 0; while (cond) { __builtin_amdgcn_s_sleep(1); \
;     if ((++_sp & 255u) == 0u) { if (xb_ld(&(bar)[XB_TMO])) break; if (_sp > XB_SPIN_CAP) { atomicAdd(&(bar)[XB_TMO], 1u); break; } } } } while (0)
; __device__ __forceinline__ void xcd_barrier(const XcdBarrier& b) {
;     ...
;         const unsigned old = xb_add(&bar[XB_XSUB(b.x)], 1u);
;         const unsigned gen = old / nloc;
;         if (old + 1u == (gen + 1u) * nloc) {
;             __builtin_amdgcn_fence(__ATOMIC_RELEASE, "agent");
;             asm volatile("s_waitcnt vmcnt(0)" ::: "memory");
;             const unsigned og = xb_add(&bar[XB_TOP], 1u);
;             const unsigned tg = og / nx;
;             if (og + 1u == (tg + 1u) * nx) xb_add(&bar[XB_TOPGEN], 1u);
;             else XB_SPIN(xb_ld(&bar[XB_TOPGEN]) == tg, bar);
;             __builtin_amdgcn_fence(__ATOMIC_ACQUIRE, "agent");
;             xb_add(&bar[XB_XGEN(b.x)], 1u);
;             asm volatile("s_waitcnt vmcnt(0)" ::: "memory");
;         } else {
;             XB_SPIN(xb_ld(&bar[XB_XGEN(b.x)]) == gen, bar);
.LBB0_322:
	s_or_b64 exec, exec, s[2:3]
	v_cvt_f32_u32_e32 v4, v2
	s_waitcnt vmcnt(0)
	v_readfirstlane_b32 s2, v3
	v_sub_u32_e32 v3, 0, v2
	v_rcp_iflag_f32_e32 v4, v4
	v_add_u32_e32 v5, s2, v1
	v_mul_f32_e32 v4, 0x4f7ffffe, v4
	v_cvt_u32_f32_e32 v4, v4
	v_mul_lo_u32 v1, v3, v4
	v_mul_hi_u32 v1, v4, v1
	v_add_u32_e32 v1, v4, v1
	v_mul_hi_u32 v1, v5, v1
	v_mul_lo_u32 v3, v1, v2
	v_sub_u32_e32 v3, v5, v3
	v_add_u32_e32 v4, 1, v1
	v_cmp_ge_u32_e32 vcc, v3, v2
	s_nop 1
	v_cndmask_b32_e32 v1, v1, v4, vcc
	v_sub_u32_e32 v4, v3, v2
	v_cndmask_b32_e32 v3, v3, v4, vcc
	v_add_u32_e32 v4, 1, v1
	v_cmp_ge_u32_e32 vcc, v3, v2
	v_add_u32_e32 v3, 1, v5
	s_nop 0
	v_cndmask_b32_e32 v1, v1, v4, vcc
	v_mul_lo_u32 v4, v2, v1
	v_add_u32_e32 v2, v4, v2
	v_cmp_ne_u32_e32 vcc, v3, v2
	s_and_saveexec_b64 s[2:3], vcc
	s_xor_b64 s[2:3], exec, s[2:3]
	s_cbranch_execz .LBB0_336
	v_readlane_b32 s6, v254, 62
	v_readlane_b32 s7, v254, 63
	s_waitcnt lgkmcnt(0)
	s_nop 3
	buffer_inv sc1
	global_load_dword v0, v193, s[6:7] sc1
	s_waitcnt vmcnt(0)
	v_cmp_eq_u32_e32 vcc, v0, v1
	s_and_saveexec_b64 s[38:39], vcc
	s_cbranch_execz .LBB0_335
	s_mov_b32 s5, 1
	s_mov_b64 s[40:41], 0
	s_branch .LBB0_326

; __device__ __forceinline__ unsigned xb_ld(unsigned* p)              { return __hip_atomic_load(p, __ATOMIC_RELAXED, __HIP_MEMORY_SCOPE_AGENT); }
; #define XB_SPIN(cond, bar) do { unsigned _sp = 0; while (cond) { __builtin_amdgcn_s_sleep(1); \
;     if ((++_sp & 255u) == 0u) { if (xb_ld(&(bar)[XB_TMO])) break; if (_sp > XB_SPIN_CAP) { atomicAdd(&(bar)[XB_TMO], 1u); break; } } } } while (0)
; __device__ __forceinline__ void xcd_barrier(const XcdBarrier& b) {
;     ...
;             XB_SPIN(xb_ld(&bar[XB_XGEN(b.x)]) == gen, bar);
;             __builtin_amdgcn_fence(__ATOMIC_ACQUIRE, "agent");
;             asm volatile("s_waitcnt vmcnt(0)" ::: "memory");
.LBB0_335:
	s_or_b64 exec, exec, s[38:39]
	s_waitcnt vmcnt(0)
	s_nop 0
	s_waitcnt vmcnt(0)

; __device__ __forceinline__ unsigned xb_ld(unsigned* p)              { return __hip_atomic_load(p, __ATOMIC_RELAXED, __HIP_MEMORY_SCOPE_AGENT); }
; __device__ __forceinline__ unsigned xb_add(unsigned* p, unsigned v) { return __hip_atomic_fetch_add(p, v, __ATOMIC_RELAXED, __HIP_MEMORY_SCOPE_AGENT); }
; #define XB_SPIN(cond, bar) do { unsigned _sp = 0; while (cond) { __builtin_amdgcn_s_sleep(1); \
;     if ((++_sp & 255u) == 0u) { if (xb_ld(&(bar)[XB_TMO])) break; if (_sp > XB_SPIN_CAP) { atomicAdd(&(bar)[XB_TMO], 1u); break; } } } } while (0)
; __device__ __forceinline__ void xcd_barrier(const XcdBarrier& b) {
;     ...
;             const unsigned og = xb_add(&bar[XB_TOP], 1u);
;             const unsigned tg = og / nx;
;             if (og + 1u == (tg + 1u) * nx) xb_add(&bar[XB_TOPGEN], 1u);
;             else XB_SPIN(xb_ld(&bar[XB_TOPGEN]) == tg, bar);
.LBB0_339:
	s_or_b64 exec, exec, s[38:39]
	s_waitcnt vmcnt(0)
	buffer_inv sc1
	v_readfirstlane_b32 s2, v2
	v_cvt_f32_u32_e32 v2, v0
	v_sub_u32_e32 v3, 0, v0
	v_add_u32_e32 v1, s2, v1
	v_readlane_b32 s2, v255, 2
	v_rcp_iflag_f32_e32 v2, v2
	v_readlane_b32 s3, v255, 3
	s_mov_b64 s[38:39], -1
	v_mul_f32_e32 v2, 0x4f7ffffe, v2
	v_cvt_u32_f32_e32 v2, v2
	v_mul_lo_u32 v3, v3, v2
	v_mul_hi_u32 v3, v2, v3
	v_add_u32_e32 v2, v2, v3
	v_mul_hi_u32 v2, v1, v2
	v_mul_lo_u32 v3, v2, v0
	v_sub_u32_e32 v3, v1, v3
	v_cmp_ge_u32_e32 vcc, v3, v0
	v_add_u32_e32 v4, 1, v2
	v_add_u32_e32 v1, 1, v1
	v_cndmask_b32_e32 v2, v2, v4, vcc
	v_sub_u32_e32 v4, v3, v0
	v_cndmask_b32_e32 v3, v3, v4, vcc
	v_cmp_ge_u32_e32 vcc, v3, v0
	v_add_u32_e32 v3, 1, v2
	s_nop 0
	v_cndmask_b32_e32 v2, v2, v3, vcc
	v_mul_lo_u32 v3, v0, v2
	v_add_u32_e32 v0, v3, v0
	v_cmp_ne_u32_e32 vcc, v1, v0
	v_mov_b64_e32 v[0:1], s[2:3]
	s_and_saveexec_b64 s[2:3], vcc
	s_cbranch_execz .LBB0_351
	v_readlane_b32 s6, v255, 2
	v_readlane_b32 s7, v255, 3
	s_mov_b64 s[40:41], 0
	s_nop 3
	global_load_dword v0, v193, s[6:7] sc1
	s_waitcnt vmcnt(0)
	v_cmp_eq_u32_e32 vcc, v0, v2
	s_and_saveexec_b64 s[38:39], vcc
	s_cbranch_execz .LBB0_350
	s_mov_b32 s5, 1
	s_branch .LBB0_343

; __device__ __forceinline__ unsigned xb_add(unsigned* p, unsigned v) { return __hip_atomic_fetch_add(p, v, __ATOMIC_RELAXED, __HIP_MEMORY_SCOPE_AGENT); }
; __device__ __forceinline__ void xcd_barrier(const XcdBarrier& b) {
;     ...
;             __builtin_amdgcn_fence(__ATOMIC_ACQUIRE, "agent");
;             xb_add(&bar[XB_XGEN(b.x)], 1u);
;             asm volatile("s_waitcnt vmcnt(0)" ::: "memory");
.LBB0_353:
	s_or_b64 exec, exec, s[2:3]
	s_mov_b64 s[2:3], exec
	v_mbcnt_lo_u32_b32 v0, s2, 0
	v_mbcnt_hi_u32_b32 v0, s3, v0
	v_cmp_eq_u32_e32 vcc, 0, v0
	s_waitcnt vmcnt(0)
	s_nop 0
	s_and_saveexec_b64 s[38:39], vcc
	s_cbranch_execz .LBB0_355
	s_bcnt1_i32_b64 s2, s[2:3]
	v_mov_b32_e32 v0, s2
	v_readlane_b32 s2, v254, 62
	v_readlane_b32 s3, v254, 63
	s_nop 4
	global_atomic_add v193, v0, s[2:3]

; __device__ __forceinline__ unsigned xb_ld(unsigned* p)              { return __hip_atomic_load(p, __ATOMIC_RELAXED, __HIP_MEMORY_SCOPE_AGENT); }
; __device__ __forceinline__ unsigned xb_add(unsigned* p, unsigned v) { return __hip_atomic_fetch_add(p, v, __ATOMIC_RELAXED, __HIP_MEMORY_SCOPE_AGENT); }
; #define XB_SPIN(cond, bar) do { unsigned _sp = 0; while (cond) { __builtin_amdgcn_s_sleep(1); \
;     if ((++_sp & 255u) == 0u) { if (xb_ld(&(bar)[XB_TMO])) break; if (_sp > XB_SPIN_CAP) { atomicAdd(&(bar)[XB_TMO], 1u); break; } } } } while (0)
; __device__ __forceinline__ void xcd_barrier(const XcdBarrier& b) {
;     ...
;         const unsigned old = xb_add(&bar[XB_XSUB(b.x)], 1u);
;         const unsigned gen = old / nloc;
;         if (old + 1u == (gen + 1u) * nloc) {
;             __builtin_amdgcn_fence(__ATOMIC_RELEASE, "agent");
;             asm volatile("s_waitcnt vmcnt(0)" ::: "memory");
;             const unsigned og = xb_add(&bar[XB_TOP], 1u);
;             const unsigned tg = og / nx;
;             if (og + 1u == (tg + 1u) * nx) xb_add(&bar[XB_TOPGEN], 1u);
;             else XB_SPIN(xb_ld(&bar[XB_TOPGEN]) == tg, bar);
;             __builtin_amdgcn_fence(__ATOMIC_ACQUIRE, "agent");
;             xb_add(&bar[XB_XGEN(b.x)], 1u);
;             asm volatile("s_waitcnt vmcnt(0)" ::: "memory");
;         } else {
;             XB_SPIN(xb_ld(&bar[XB_XGEN(b.x)]) == gen, bar);
.LBB0_763:
	s_or_b64 exec, exec, s[2:3]
	v_cvt_f32_u32_e32 v4, v2
	s_waitcnt vmcnt(0)
	v_readfirstlane_b32 s2, v3
	v_sub_u32_e32 v3, 0, v2
	v_rcp_iflag_f32_e32 v4, v4
	v_add_u32_e32 v5, s2, v1
	v_mul_f32_e32 v4, 0x4f7ffffe, v4
	v_cvt_u32_f32_e32 v4, v4
	v_mul_lo_u32 v1, v3, v4
	v_mul_hi_u32 v1, v4, v1
	v_add_u32_e32 v1, v4, v1
	v_mul_hi_u32 v1, v5, v1
	v_mul_lo_u32 v3, v1, v2
	v_sub_u32_e32 v3, v5, v3
	v_add_u32_e32 v4, 1, v1
	v_cmp_ge_u32_e32 vcc, v3, v2
	s_nop 1
	v_cndmask_b32_e32 v1, v1, v4, vcc
	v_sub_u32_e32 v4, v3, v2
	v_cndmask_b32_e32 v3, v3, v4, vcc
	v_add_u32_e32 v4, 1, v1
	v_cmp_ge_u32_e32 vcc, v3, v2
	v_add_u32_e32 v3, 1, v5
	s_nop 0
	v_cndmask_b32_e32 v1, v1, v4, vcc
	v_mul_lo_u32 v4, v2, v1
	v_add_u32_e32 v2, v4, v2
	v_cmp_ne_u32_e32 vcc, v3, v2
	s_and_saveexec_b64 s[2:3], vcc
	s_xor_b64 s[2:3], exec, s[2:3]
	s_cbranch_execz .LBB0_777
	v_readlane_b32 s4, v254, 62
	v_readlane_b32 s5, v254, 63
	s_waitcnt lgkmcnt(0)
	s_nop 3
	buffer_inv sc1
	global_load_dword v0, v193, s[4:5] sc1
	s_waitcnt vmcnt(0)
	v_cmp_eq_u32_e32 vcc, v0, v1
	s_and_saveexec_b64 s[38:39], vcc
	s_cbranch_execz .LBB0_776
	s_mov_b32 s4, 1
	s_mov_b64 s[40:41], 0
	s_branch .LBB0_767

; __device__ __forceinline__ unsigned xb_ld(unsigned* p)              { return __hip_atomic_load(p, __ATOMIC_RELAXED, __HIP_MEMORY_SCOPE_AGENT); }
; __device__ __forceinline__ unsigned xb_add(unsigned* p, unsigned v) { return __hip_atomic_fetch_add(p, v, __ATOMIC_RELAXED, __HIP_MEMORY_SCOPE_AGENT); }
; #define XB_SPIN(cond, bar) do { unsigned _sp = 0; while (cond) { __builtin_amdgcn_s_sleep(1); \
;     if ((++_sp & 255u) == 0u) { if (xb_ld(&(bar)[XB_TMO])) break; if (_sp > XB_SPIN_CAP) { atomicAdd(&(bar)[XB_TMO], 1u); break; } } } } while (0)
; __device__ __forceinline__ void xcd_barrier(const XcdBarrier& b) {
;     ...
;             const unsigned og = xb_add(&bar[XB_TOP], 1u);
;             const unsigned tg = og / nx;
;             if (og + 1u == (tg + 1u) * nx) xb_add(&bar[XB_TOPGEN], 1u);
;             else XB_SPIN(xb_ld(&bar[XB_TOPGEN]) == tg, bar);
.LBB0_780:
	s_or_b64 exec, exec, s[38:39]
	s_waitcnt vmcnt(0)
	buffer_inv sc1
	v_readfirstlane_b32 s2, v2
	v_cvt_f32_u32_e32 v2, v0
	v_sub_u32_e32 v3, 0, v0
	v_add_u32_e32 v1, s2, v1
	v_readlane_b32 s2, v255, 2
	v_rcp_iflag_f32_e32 v2, v2
	v_readlane_b32 s3, v255, 3
	s_mov_b64 s[38:39], -1
	v_mul_f32_e32 v2, 0x4f7ffffe, v2
	v_cvt_u32_f32_e32 v2, v2
	v_mul_lo_u32 v3, v3, v2
	v_mul_hi_u32 v3, v2, v3
	v_add_u32_e32 v2, v2, v3
	v_mul_hi_u32 v2, v1, v2
	v_mul_lo_u32 v3, v2, v0
	v_sub_u32_e32 v3, v1, v3
	v_cmp_ge_u32_e32 vcc, v3, v0
	v_add_u32_e32 v4, 1, v2
	v_add_u32_e32 v1, 1, v1
	v_cndmask_b32_e32 v2, v2, v4, vcc
	v_sub_u32_e32 v4, v3, v0
	v_cndmask_b32_e32 v3, v3, v4, vcc
	v_cmp_ge_u32_e32 vcc, v3, v0
	v_add_u32_e32 v3, 1, v2
	s_nop 0
	v_cndmask_b32_e32 v2, v2, v3, vcc
	v_mul_lo_u32 v3, v0, v2
	v_add_u32_e32 v0, v3, v0
	v_cmp_ne_u32_e32 vcc, v1, v0
	v_mov_b64_e32 v[0:1], s[2:3]
	s_and_saveexec_b64 s[2:3], vcc
	s_cbranch_execz .LBB0_792
	v_readlane_b32 s4, v255, 2
	v_readlane_b32 s5, v255, 3
	s_mov_b64 s[40:41], 0
	s_nop 3
	global_load_dword v0, v193, s[4:5] sc1
	s_waitcnt vmcnt(0)
	v_cmp_eq_u32_e32 vcc, v0, v2
	s_and_saveexec_b64 s[38:39], vcc
	s_cbranch_execz .LBB0_791
	s_mov_b32 s4, 1
	s_branch .LBB0_784

; __device__ __forceinline__ unsigned xb_add(unsigned* p, unsigned v) { return __hip_atomic_fetch_add(p, v, __ATOMIC_RELAXED, __HIP_MEMORY_SCOPE_AGENT); }
; __device__ __forceinline__ void xcd_barrier(const XcdBarrier& b) {
;     ...
;             __builtin_amdgcn_fence(__ATOMIC_ACQUIRE, "agent");
;             xb_add(&bar[XB_XGEN(b.x)], 1u);
;             asm volatile("s_waitcnt vmcnt(0)" ::: "memory");
.LBB0_794:
	s_or_b64 exec, exec, s[2:3]
	s_mov_b64 s[2:3], exec
	v_mbcnt_lo_u32_b32 v0, s2, 0
	v_mbcnt_hi_u32_b32 v0, s3, v0
	v_cmp_eq_u32_e32 vcc, 0, v0
	s_waitcnt vmcnt(0)
	s_nop 0
	s_and_saveexec_b64 s[38:39], vcc
	s_cbranch_execz .LBB0_123
	s_bcnt1_i32_b64 s2, s[2:3]
	v_mov_b32_e32 v0, s2
	v_readlane_b32 s2, v254, 62
	v_readlane_b32 s3, v254, 63
	s_nop 4
	global_atomic_add v193, v0, s[2:3]
	s_branch .LBB0_123
